# attention: next item's K/V/Q/bias loads prefetched into free VGPRs during the current item's compute (queue head two items ahead)
# baseline (speedup 1.0000x reference)
; #define LAS __attribute__((address_space(3)))
; __device__ __forceinline__ void attn_phase(const Params& p, LAS unsigned char* lds) {
;     const int tid = threadIdx.x, lane = tid & 63, w = __builtin_amdgcn_readfirstlane(tid >> 6), fr = lane & 15, fq = lane >> 4;
;     LAS unsigned char* Ks = lds;
;     LAS unsigned char* Vs = lds + 73728;
;     LAS float* rp = (LAS float*)(lds + 147456);
;     volatile LAS unsigned* slot = (volatile LAS unsigned*)(lds + 147456 + 2048);
;     const bf16_t* QH = (const bf16_t*)(p.ws + WS_QK); const bf16_t* KH = (const bf16_t*)(p.ws + WS_QK + (16u << 20)); const bf16_t* VTA = (const bf16_t*)(p.ws + WS_VTA);
;     bf16_t* YCAT = (bf16_t*)(p.ws + WS_YCAT); float* SSQNA = (float*)(p.ws + WS_SSQ1 + 512 * 1024);
;     const float sc2 = 0.125f * 1.4426950408889634f;
;     unsigned* ctr = (unsigned*)(p.ws + WS_BAR) + 3584;
;     const int ri = w >> 2, qb = w & 3, q0 = qb * 16, kc0 = min(max(q0 - 8, 0), 32);
;     const int kperm = 8 * (fr >> 2) + (fr & 3);
;     for (;;) {
;         __syncthreads();
;         if (tid == 0) slot[0] = __hip_atomic_fetch_add(ctr, 1u, __ATOMIC_RELAXED, __HIP_MEMORY_SCOPE_AGENT);
;         __syncthreads();
;         const int item = (int)slot[0];
;         if (item >= 1024) break;
;         const int b = item >> 7, h = (item >> 4) & 7, r0 = (item & 15) * 2, R0 = min(max(r0 - 4, 0), 24);
;         const int r = r0 + ri, rs = min(max(r - 4, 0), 24), j0 = rs - R0;
;         const int tq = b * SEQ + r * 64 + q0 + fr;
;         const bf16_t* qp = QH + ((size_t)(b * 8 + h) * SEQ + r * 64 + q0 + fr) * 64 + fq * 8;
;         const bf16x8 qf0 = *(const bf16x8*)qp, qf1 = *(const bf16x8*)(qp + 32);
;         for (int u = tid; u < 465; u += NTHREADS) rp[u] = p.rpb[h * 465 + u] * 1.4426950408889634f;
;         { const int t = tid >> 3, c = tid & 7; const unsigned dstk = (unsigned)(t * 128 + ((c ^ (((t >> 1) & 1) | (((t >> 3) & 3) << 1))) << 4)), dstv = (unsigned)(t * 128 + ((c ^ ((t >> 1) & 7)) << 4));
;           u32x4 kv[9], vv[9];
; #pragma unroll
;           for (int j = 0; j < 9; ++j) { const int srow = min(R0 + j, 31);
;               kv[j] = *(const u32x4*)(KH + ((size_t)(b * 8 + h) * SEQ + srow * 64 + t) * 64 + c * 8);
;               vv[j] = *(const u32x4*)(VTA + ((size_t)((b * 8 + h) * 32 + srow) * 64 + t) * 64 + c * 8); }
; #pragma unroll
.LBB0_335:
	s_waitcnt lgkmcnt(0)
	s_add_u32 s12, s34, 0x180000
	s_addc_u32 s13, s35, 0
	v_readfirstlane_b32 s0, v170
	s_add_u32 s14, s34, 0x83800
	s_addc_u32 s15, s35, 0
	s_lshr_b32 s10, s0, 8
	s_lshr_b32 s0, s0, 2
	s_and_b32 s0, s0, 48
	v_sub_u32_e64 v0, s0, 8 clamp
	v_min_u32_e32 v4, 32, v0
	v_lshlrev_b32_e32 v0, 1, v170
	v_and_b32_e32 v1, 3, v170
	v_mov_b32_e32 v31, 0
	v_lshlrev_b32_e32 v30, 1, v130
	v_and_or_b32 v5, v0, 24, v1
	v_or_b32_e32 v28, s0, v131
	v_lshl_add_u64 v[0:1], s[34:35], 0, v[30:31]
	s_mov_b64 s[0:1], 0x5f00000
	v_lshl_add_u64 v[32:33], v[0:1], 0, s[0:1]
	v_and_b32_e32 v1, 7, v170
	v_bfe_u32 v2, v170, 4, 1
	v_and_b32_e32 v3, 6, v133
	v_bitop3_b32 v2, v2, v1, v3 bitop3:0x36
	v_lshlrev_b32_e32 v6, 4, v2
	v_xor_b32_e32 v2, v172, v170
	v_lshlrev_b32_e32 v2, 4, v2
	v_lshlrev_b32_e32 v30, 4, v1
	v_lshlrev_b32_e32 v0, 7, v128
	v_and_b32_e32 v7, 0x70, v2
	v_lshl_add_u64 v[2:3], s[34:35], 0, v[30:31]
	s_mov_b64 s[4:5], 0x6f00000
	v_mov_b32_e32 v1, v31
	v_lshl_add_u64 v[34:35], v[2:3], 0, s[4:5]
	v_lshl_add_u64 v[2:3], s[34:35], 0, v[0:1]
	v_lshl_add_u64 v[2:3], v[2:3], 0, v[30:31]
	s_mov_b64 s[4:5], 0x7f00000
	v_add_u32_e32 v1, v4, v5
	v_lshl_add_u64 v[36:37], v[2:3], 0, s[4:5]
	v_lshrrev_b32_e32 v3, 2, v1
	v_bfe_u32 v2, v170, 1, 1
	v_and_b32_e32 v3, 6, v3
	v_bitop3_b32 v5, v3, v129, v2 bitop3:0x36
	v_lshlrev_b32_e32 v39, 4, v5
	v_or_b32_e32 v5, 4, v129
	s_add_i32 s4, 0, 0x12000
	v_bitop3_b32 v2, v3, v5, v2 bitop3:0x36
	v_add_u32_e32 v3, v4, v130
	v_lshrrev_b32_e32 v4, 3, v4
	v_add3_u32 v29, 0, v0, v6
	v_add3_u32 v38, s4, v0, v7
	v_lshrrev_b32_e32 v0, 1, v170
	v_lshlrev_b32_e32 v40, 4, v2
	v_sub_u32_e64 v2, v28, 8 clamp
	v_add_u32_e32 v4, v4, v129
	v_min_u32_e32 v2, 48, v2
	v_bitop3_b32 v0, v4, v0, 7 bitop3:0x78
	v_add_u32_e32 v5, 16, v2
	v_lshlrev_b32_e32 v6, 7, v131
	v_lshlrev_b32_e32 v0, 4, v0
	s_add_i32 s6, 0, 0x24000
	v_add3_u32 v41, s4, v6, v0
	v_lshl_add_u32 v42, v170, 2, s6
	v_cmp_ge_u32_e32 vcc, v3, v2
	v_cmp_lt_u32_e64 s[6:7], v3, v5
	v_sub_u32_e32 v6, v3, v28
	v_mov_b32_e32 v4, 0xf149f2ca
	s_and_b64 s[6:7], vcc, s[6:7]
	v_med3_i32 v46, v6, -15, 15
	v_or_b32_e32 v6, 1, v3
	v_cndmask_b32_e64 v45, v4, 0, s[6:7]
	v_cmp_ge_u32_e32 vcc, v6, v2
	v_cmp_lt_u32_e64 s[6:7], v6, v5
	v_sub_u32_e32 v6, v6, v28
	s_and_b64 s[6:7], vcc, s[6:7]
	v_med3_i32 v48, v6, -15, 15
	v_or_b32_e32 v6, 2, v3
	v_cndmask_b32_e64 v47, v4, 0, s[6:7]
	v_cmp_ge_u32_e32 vcc, v6, v2
	v_cmp_lt_u32_e64 s[6:7], v6, v5
	v_sub_u32_e32 v6, v6, v28
	s_and_b64 s[6:7], vcc, s[6:7]
	v_med3_i32 v50, v6, -15, 15
	v_or_b32_e32 v6, 3, v3
	v_cndmask_b32_e64 v49, v4, 0, s[6:7]
	v_cmp_ge_u32_e32 vcc, v6, v2
	v_cmp_lt_u32_e64 s[6:7], v6, v5
	v_sub_u32_e32 v6, v6, v28
	s_and_b64 s[6:7], vcc, s[6:7]
	v_med3_i32 v52, v6, -15, 15
	v_or_b32_e32 v6, 4, v3
	v_cndmask_b32_e64 v51, v4, 0, s[6:7]
	v_cmp_ge_u32_e32 vcc, v6, v2
	v_cmp_lt_u32_e64 s[6:7], v6, v5
	v_sub_u32_e32 v6, v6, v28
	s_and_b64 s[6:7], vcc, s[6:7]
	v_med3_i32 v54, v6, -15, 15
	v_or_b32_e32 v6, 5, v3
	v_cndmask_b32_e64 v53, v4, 0, s[6:7]
	v_cmp_ge_u32_e32 vcc, v6, v2
	v_cmp_lt_u32_e64 s[6:7], v6, v5
	v_sub_u32_e32 v6, v6, v28
	s_and_b64 s[6:7], vcc, s[6:7]
	v_med3_i32 v56, v6, -15, 15
	v_or_b32_e32 v6, 6, v3
	v_cndmask_b32_e64 v55, v4, 0, s[6:7]
	v_cmp_ge_u32_e32 vcc, v6, v2
	v_cmp_lt_u32_e64 s[6:7], v6, v5
	s_and_b64 s[6:7], vcc, s[6:7]
	v_or_b32_e32 v3, 7, v3
	v_lshlrev_b32_e32 v0, 2, v129
	v_cndmask_b32_e64 v57, v4, 0, s[6:7]
	v_cmp_ge_u32_e32 vcc, v3, v2
	v_cmp_lt_u32_e64 s[6:7], v3, v5
	s_movk_i32 s0, 0x1d1
	v_sub_u32_e32 v6, v6, v28
	s_and_b64 s[6:7], vcc, s[6:7]
	v_sub_u32_e32 v2, v3, v28
	v_lshlrev_b32_e32 v30, 1, v0
	v_mbcnt_lo_u32_b32 v0, -1, 0
	v_cmp_gt_u32_e64 s[0:1], s0, v170
	s_mov_b32 s17, 0
	v_cmp_eq_u32_e64 s[4:5], 0, v129
	v_add_u32_e32 v43, 0x10000, v29
	v_add_u32_e32 v44, 0x10000, v38
	s_mov_b32 s11, 0xf149f2ca
	v_med3_i32 v58, v6, -15, 15
	v_cndmask_b32_e64 v59, v4, 0, s[6:7]
	v_med3_i32 v60, v2, -15, 15
	v_lshl_add_u32 v61, v1, 7, 0
	s_add_i32 s33, 0, 0x24800
	s_movk_i32 s40, 0x3ff
	s_mov_b64 s[6:7], 0xb200400
	s_mov_b32 s41, 0xb200000
	v_mbcnt_hi_u32_b32 v62, -1, v0
	s_and_saveexec_b64 s[98:99], s[58:59]
	s_cbranch_execz .Lattn_pf_a
	v_mov_b32_e32 v243, 1
	global_atomic_add v242, v31, v243, s[14:15] sc0
	global_atomic_add v252, v31, v243, s[14:15] sc0
	s_waitcnt vmcnt(0)
	v_mov_b32_e32 v1, s33
	ds_write_b32 v1, v242 offset:4
; __device__ __forceinline__ void attn_phase(const Params& p, LAS unsigned char* lds) {
;     ...
;         const int b = item >> 7, h = (item >> 4) & 7, r0 = (item & 15) * 2, R0 = min(max(r0 - 4, 0), 24);
;         const int r = r0 + ri, rs = min(max(r - 4, 0), 24), j0 = rs - R0;
;         const int tq = b * SEQ + r * 64 + q0 + fr;
;         const bf16_t* qp = QH + ((size_t)(b * 8 + h) * SEQ + r * 64 + q0 + fr) * 64 + fq * 8;
;         const bf16x8 qf0 = *(const bf16x8*)qp, qf1 = *(const bf16x8*)(qp + 32);
;         for (int u = tid; u < 465; u += NTHREADS) rp[u] = p.rpb[h * 465 + u] * 1.4426950408889634f;
;         { const int t = tid >> 3, c = tid & 7; const unsigned dstk = (unsigned)(t * 128 + ((c ^ (((t >> 1) & 1) | (((t >> 3) & 3) << 1))) << 4)), dstv = (unsigned)(t * 128 + ((c ^ ((t >> 1) & 7)) << 4));
;           u32x4 kv[9], vv[9];
; #pragma unroll
;           for (int j = 0; j < 9; ++j) { const int srow = min(R0 + j, 31);
;               kv[j] = *(const u32x4*)(KH + ((size_t)(b * 8 + h) * SEQ + srow * 64 + t) * 64 + c * 8);
;               vv[j] = *(const u32x4*)(VTA + ((size_t)((b * 8 + h) * 32 + srow) * 64 + t) * 64 + c * 8); }
.Lattn_pf_a:
	s_or_b64 exec, exec, s[98:99]
	s_waitcnt vmcnt(0) lgkmcnt(0)
	s_barrier
	v_mov_b32_e32 v0, s33
	ds_read_b32 v244, v0 offset:4
	s_waitcnt lgkmcnt(0)
	v_min_u32_e32 v232, 0x3ff, v244
	v_mov_b32_e32 v229, 0
	v_lshrrev_b32_e32 v233, 4, v232
	v_and_b32_e32 v234, 15, v232
	v_lshlrev_b32_e32 v234, 1, v234
	v_sub_u32_e64 v235, v234, 4 clamp
	v_min_u32_e32 v235, 24, v235
	v_add_u32_e32 v236, s10, v234
	v_lshlrev_b32_e32 v228, 11, v233
	v_lshl_add_u32 v228, v236, 6, v228
	v_add_u32_e32 v228, v228, v28
	v_lshlrev_b32_e32 v228, 7, v228
	v_lshl_add_u64 v[226:227], v[32:33], 0, v[228:229]
	global_load_dwordx4 v[212:215], v[226:227], off
	global_load_dwordx4 v[216:219], v[226:227], off offset:64
	v_and_b32_e32 v236, 7, v233
	v_mul_u32_u24_e32 v236, 0x1d1, v236
	v_add_lshl_u32 v236, v236, v170, 2
	s_mov_b64 exec, s[0:1]
	global_load_dword v220, v236, s[50:51]
	s_mov_b64 exec, -1
	v_cmp_ne_u32_e32 vcc, 24, v235
	v_lshlrev_b32_e32 v228, 18, v233
	v_lshl_add_u32 v228, v235, 13, v228
	v_mov_b32_e32 v231, 0x2000
	v_lshl_add_u32 v238, v128, 7, v228
	v_mov_b32_e32 v239, 0
	v_cndmask_b32_e32 v230, v229, v231, vcc
	v_mov_b32_e32 v231, 0
	v_lshl_add_u64 v[222:223], v[34:35], 0, v[238:239]
	v_lshl_add_u64 v[224:225], v[36:37], 0, v[228:229]
	s_mov_b64 s[98:99], 0x2000
	global_load_dwordx4 v[134:137], v[222:223], off
	global_load_dwordx4 v[138:141], v[224:225], off
	v_lshl_add_u64 v[222:223], v[222:223], 0, s[98:99]
	v_lshl_add_u64 v[224:225], v[224:225], 0, s[98:99]
	global_load_dwordx4 v[142:145], v[222:223], off
	global_load_dwordx4 v[146:149], v[224:225], off
	v_lshl_add_u64 v[222:223], v[222:223], 0, s[98:99]
	v_lshl_add_u64 v[224:225], v[224:225], 0, s[98:99]
	global_load_dwordx4 v[150:153], v[222:223], off
	global_load_dwordx4 v[154:157], v[224:225], off
	v_lshl_add_u64 v[222:223], v[222:223], 0, s[98:99]
	v_lshl_add_u64 v[224:225], v[224:225], 0, s[98:99]
	global_load_dwordx4 v[158:161], v[222:223], off
	global_load_dwordx4 v[162:165], v[224:225], off
	v_lshl_add_u64 v[222:223], v[222:223], 0, s[98:99]
	v_lshl_add_u64 v[224:225], v[224:225], 0, s[98:99]
	global_load_dwordx4 v[166:169], v[222:223], off
	global_load_dwordx4 v[176:179], v[224:225], off
	v_lshl_add_u64 v[222:223], v[222:223], 0, s[98:99]
	v_lshl_add_u64 v[224:225], v[224:225], 0, s[98:99]
	global_load_dwordx4 v[180:183], v[222:223], off
	global_load_dwordx4 v[184:187], v[224:225], off
	v_lshl_add_u64 v[222:223], v[222:223], 0, s[98:99]
	v_lshl_add_u64 v[224:225], v[224:225], 0, s[98:99]
	global_load_dwordx4 v[188:191], v[222:223], off
	global_load_dwordx4 v[192:195], v[224:225], off
	v_lshl_add_u64 v[222:223], v[222:223], 0, s[98:99]
	v_lshl_add_u64 v[224:225], v[224:225], 0, s[98:99]
	global_load_dwordx4 v[196:199], v[222:223], off
	global_load_dwordx4 v[200:203], v[224:225], off
	v_lshl_add_u64 v[222:223], v[222:223], 0, v[230:231]
	v_lshl_add_u64 v[224:225], v[224:225], 0, v[230:231]
	global_load_dwordx4 v[204:207], v[222:223], off
	global_load_dwordx4 v[208:211], v[224:225], off
	s_waitcnt vmcnt(0)
	s_branch .LBB0_338

; #define LAS __attribute__((address_space(3)))
; __device__ __forceinline__ void attn_phase(const Params& p, LAS unsigned char* lds) {
;     ...
;         const int item = (int)slot[0];
;         if (item >= 1024) break;
;         const int b = item >> 7, h = (item >> 4) & 7, r0 = (item & 15) * 2, R0 = min(max(r0 - 4, 0), 24);
;         const int r = r0 + ri, rs = min(max(r - 4, 0), 24), j0 = rs - R0;
;         const int tq = b * SEQ + r * 64 + q0 + fr;
;         const bf16_t* qp = QH + ((size_t)(b * 8 + h) * SEQ + r * 64 + q0 + fr) * 64 + fq * 8;
;         const bf16x8 qf0 = *(const bf16x8*)qp, qf1 = *(const bf16x8*)(qp + 32);
;         for (int u = tid; u < 465; u += NTHREADS) rp[u] = p.rpb[h * 465 + u] * 1.4426950408889634f;
;         { const int t = tid >> 3, c = tid & 7; const unsigned dstk = (unsigned)(t * 128 + ((c ^ (((t >> 1) & 1) | (((t >> 3) & 3) << 1))) << 4)), dstv = (unsigned)(t * 128 + ((c ^ ((t >> 1) & 7)) << 4));
;           u32x4 kv[9], vv[9];
; #pragma unroll
;           for (int j = 0; j < 9; ++j) { const int srow = min(R0 + j, 31);
;               kv[j] = *(const u32x4*)(KH + ((size_t)(b * 8 + h) * SEQ + srow * 64 + t) * 64 + c * 8);
;               vv[j] = *(const u32x4*)(VTA + ((size_t)((b * 8 + h) * 32 + srow) * 64 + t) * 64 + c * 8); }
; #pragma unroll
;           for (int j = 0; j < 9; ++j) { *(LAS u32x4*)(Ks + j * 8192 + dstk) = kv[j]; *(LAS u32x4*)(Vs + j * 8192 + dstv) = vv[j]; } }
.LBB0_338:
	s_waitcnt vmcnt(26)
	s_barrier
	s_and_saveexec_b64 s[20:21], s[58:59]
	s_cbranch_execz .LBB0_342
	v_mov_b32_e32 v1, s33
	ds_write_b32 v1, v242
	ds_write_b32 v1, v252 offset:4
.LBB0_342:
	s_or_b64 exec, exec, s[20:21]
	v_mov_b32_e32 v0, s33
	s_waitcnt lgkmcnt(0)
	s_barrier
	ds_read_b32 v244, v0 offset:4
	ds_read_b32 v0, v0
	s_mov_b64 s[20:21], -1
	s_waitcnt lgkmcnt(0)
	v_cmp_lt_i32_e32 vcc, s40, v0
	v_readfirstlane_b32 s16, v0
	s_cbranch_vccnz .LBB0_337
	s_ashr_i32 s43, s16, 7
	s_bfe_u32 s42, s16, 0x30004
	s_lshl_b32 s16, s16, 1
	s_lshl_b32 s20, s43, 3
	s_and_b32 s16, s16, 30
	s_or_b32 s20, s20, s42
	s_add_i32 s45, s16, s10
	s_ashr_i32 s21, s20, 31
	s_lshl_b32 s44, s45, 6
	s_lshl_b64 s[26:27], s[20:21], 11
	s_add_u32 s21, s26, s44
	s_addc_u32 s38, s27, 0
	v_mov_b32_e32 v1, s38
	v_or_b32_e32 v0, s21, v28
	v_lshlrev_b64 v[0:1], 7, v[0:1]
	v_lshl_add_u64 v[0:1], v[32:33], 0, v[0:1]
	s_and_saveexec_b64 s[38:39], s[0:1]
	s_cbranch_execz .LBB0_345
	s_mul_i32 s21, s42, 0x1d1
	v_add_lshl_u32 v0, s21, v170, 2
.LBB0_345:
	s_or_b64 exec, exec, s[38:39]
	v_sub_u32_e64 v0, s16, 4 clamp
	v_or_b32_e32 v108, s26, v128
	v_readfirstlane_b32 s38, v0
	s_min_u32 s39, s38, 24
	s_lshl_b32 s26, s20, 5
	s_or_b32 s20, s39, s26
	s_ashr_i32 s21, s20, 31
	s_lshl_b64 s[20:21], s[20:21], 13
	v_lshl_add_u64 v[8:9], v[36:37], 0, s[20:21]
	s_or_b32 s20, s39, 1
	s_lshl_b32 s16, s20, 6
	s_or_b32 s20, s20, s26
	s_ashr_i32 s21, s20, 31
	s_lshl_b64 s[20:21], s[20:21], 13
	v_mov_b32_e32 v109, s27
	v_lshl_add_u64 v[20:21], v[36:37], 0, s[20:21]
	s_add_i32 s20, s39, 2
	v_lshl_add_u64 v[16:17], v[108:109], 0, s[16:17]
	s_lshl_b32 s16, s20, 6
	s_or_b32 s20, s20, s26
	s_ashr_i32 s21, s20, 31
	s_lshl_b64 s[20:21], s[20:21], 13
	v_lshl_add_u64 v[64:65], v[36:37], 0, s[20:21]
	s_add_i32 s20, s39, 3
	v_lshl_add_u64 v[24:25], v[108:109], 0, s[16:17]
	s_lshl_b32 s16, s20, 6
	s_or_b32 s20, s20, s26
	s_ashr_i32 s21, s20, 31
	s_lshl_b64 s[20:21], s[20:21], 13
	v_lshl_add_u64 v[72:73], v[36:37], 0, s[20:21]
	s_add_i32 s20, s39, 4
	v_lshl_add_u64 v[68:69], v[108:109], 0, s[16:17]
	s_lshl_b32 s16, s20, 6
	s_or_b32 s20, s20, s26
	s_ashr_i32 s21, s20, 31
	s_lshl_b64 s[20:21], s[20:21], 13
	v_lshl_add_u64 v[80:81], v[36:37], 0, s[20:21]
	s_add_i32 s20, s39, 5
	v_lshl_add_u64 v[76:77], v[108:109], 0, s[16:17]
	s_lshl_b32 s16, s20, 6
	s_or_b32 s20, s20, s26
	s_ashr_i32 s21, s20, 31
	s_lshl_b64 s[20:21], s[20:21], 13
	v_lshl_add_u64 v[88:89], v[36:37], 0, s[20:21]
	s_add_i32 s20, s39, 6
	v_lshl_add_u64 v[84:85], v[108:109], 0, s[16:17]
	s_lshl_b32 s16, s20, 6
	s_or_b32 s20, s20, s26
	s_ashr_i32 s21, s20, 31
	s_lshl_b64 s[20:21], s[20:21], 13
	v_lshl_add_u64 v[96:97], v[36:37], 0, s[20:21]
	s_add_i32 s20, s39, 7
	v_lshl_add_u64 v[92:93], v[108:109], 0, s[16:17]
	s_lshl_b32 s16, s20, 6
	s_or_b32 s20, s20, s26
	s_ashr_i32 s21, s20, 31
	v_lshl_add_u64 v[100:101], v[108:109], 0, s[16:17]
	s_lshl_b64 s[20:21], s[20:21], 13
	s_min_u32 s16, s38, 23
	v_lshl_add_u64 v[104:105], v[36:37], 0, s[20:21]
	s_add_i32 s20, s16, 8
	s_lshl_b32 s16, s20, 6
	s_or_b32 s20, s20, s26
	v_lshl_or_b32 v0, s39, 6, v108
	v_mov_b32_e32 v1, s27
	v_lshl_add_u64 v[108:109], v[108:109], 0, s[16:17]
	s_ashr_i32 s21, s20, 31
	v_lshlrev_b64 v[0:1], 7, v[0:1]
	v_lshlrev_b64 v[16:17], 7, v[16:17]
	v_lshlrev_b64 v[24:25], 7, v[24:25]
	v_lshlrev_b64 v[68:69], 7, v[68:69]
	v_lshlrev_b64 v[76:77], 7, v[76:77]
	v_lshlrev_b64 v[84:85], 7, v[84:85]
	v_lshlrev_b64 v[92:93], 7, v[92:93]
	v_lshlrev_b64 v[100:101], 7, v[100:101]
	v_lshlrev_b64 v[108:109], 7, v[108:109]
	s_lshl_b64 s[20:21], s[20:21], 13
	v_lshl_add_u64 v[0:1], v[34:35], 0, v[0:1]
	v_lshl_add_u64 v[16:17], v[34:35], 0, v[16:17]
	v_lshl_add_u64 v[24:25], v[34:35], 0, v[24:25]
	v_lshl_add_u64 v[68:69], v[34:35], 0, v[68:69]
	v_lshl_add_u64 v[76:77], v[34:35], 0, v[76:77]
	v_lshl_add_u64 v[84:85], v[34:35], 0, v[84:85]
	v_lshl_add_u64 v[92:93], v[34:35], 0, v[92:93]
	v_lshl_add_u64 v[100:101], v[34:35], 0, v[100:101]
	v_lshl_add_u64 v[108:109], v[34:35], 0, v[108:109]
	v_lshl_add_u64 v[112:113], v[36:37], 0, s[20:21]
	s_max_i32 s16, s45, 4
	s_add_i32 s16, s16, -4
	s_min_u32 s20, s16, 24
	s_sub_i32 s16, s20, s39
	s_lshl_b32 s16, s16, 13
	s_sub_i32 s20, s20, s45
	s_mulk_i32 s20, 0x7c
	s_add_i32 s20, s20, 0
	s_add_i32 s20, s20, 0x24000
	v_lshl_add_u32 v118, v58, 2, s20
	v_lshl_add_u32 v119, v60, 2, s20
	s_waitcnt vmcnt(23)
	v_mov_b32_e32 v12, v212
	v_mov_b32_e32 v13, v213
	v_mov_b32_e32 v14, v214
	v_mov_b32_e32 v15, v215
	v_mov_b32_e32 v4, v216
	v_mov_b32_e32 v5, v217
	v_mov_b32_e32 v6, v218
	v_mov_b32_e32 v7, v219
	s_and_saveexec_b64 s[98:99], s[0:1]
	v_mul_f32_e32 v241, 0x3fb8aa3b, v220
	ds_write_b32 v42, v241
	s_or_b64 exec, exec, s[98:99]
	s_waitcnt vmcnt(22)
	ds_write_b128 v29, v[134:137]
	s_waitcnt vmcnt(21)
	ds_write_b128 v38, v[138:141]
	s_waitcnt vmcnt(20)
	ds_write_b128 v29, v[142:145] offset:8192
	s_waitcnt vmcnt(19)
	ds_write_b128 v38, v[146:149] offset:8192
	s_waitcnt vmcnt(18)
	ds_write_b128 v29, v[150:153] offset:16384
	s_waitcnt vmcnt(17)
	ds_write_b128 v38, v[154:157] offset:16384
	s_waitcnt vmcnt(16)
	ds_write_b128 v29, v[158:161] offset:24576
	s_waitcnt vmcnt(15)
	ds_write_b128 v38, v[162:165] offset:24576
	s_waitcnt vmcnt(14)
	ds_write_b128 v29, v[166:169] offset:32768
	s_waitcnt vmcnt(13)
	ds_write_b128 v38, v[176:179] offset:32768
	s_waitcnt vmcnt(12)
	ds_write_b128 v29, v[180:183] offset:40960
	s_waitcnt vmcnt(11)
	ds_write_b128 v38, v[184:187] offset:40960
	s_waitcnt vmcnt(10)
	ds_write_b128 v29, v[188:191] offset:49152
	s_waitcnt vmcnt(9)
	ds_write_b128 v38, v[192:195] offset:49152
	s_waitcnt vmcnt(8)
	ds_write_b128 v29, v[196:199] offset:57344
	s_waitcnt vmcnt(7)
	ds_write_b128 v38, v[200:203] offset:57344
	s_waitcnt vmcnt(6)
	ds_write_b128 v43, v[204:207]
	s_waitcnt vmcnt(5)
	ds_write_b128 v44, v[208:211]
	v_add_u32_e32 v8, s16, v61
	v_add_u32_e32 v63, v8, v39
	s_waitcnt lgkmcnt(0)
	s_barrier
	s_and_saveexec_b64 s[98:99], s[58:59]
	s_cbranch_execz .Lattn_pf_b
	v_mov_b32_e32 v242, v252
	v_mov_b32_e32 v243, 1
	global_atomic_add v252, v31, v243, s[14:15] sc0
; #define LAS __attribute__((address_space(3)))
; __device__ __forceinline__ void attn_phase(const Params& p, LAS unsigned char* lds) {
;     ...
;         const int b = item >> 7, h = (item >> 4) & 7, r0 = (item & 15) * 2, R0 = min(max(r0 - 4, 0), 24);
;         const int r = r0 + ri, rs = min(max(r - 4, 0), 24), j0 = rs - R0;
;         const int tq = b * SEQ + r * 64 + q0 + fr;
;         const bf16_t* qp = QH + ((size_t)(b * 8 + h) * SEQ + r * 64 + q0 + fr) * 64 + fq * 8;
;         const bf16x8 qf0 = *(const bf16x8*)qp, qf1 = *(const bf16x8*)(qp + 32);
;         for (int u = tid; u < 465; u += NTHREADS) rp[u] = p.rpb[h * 465 + u] * 1.4426950408889634f;
;         { const int t = tid >> 3, c = tid & 7; const unsigned dstk = (unsigned)(t * 128 + ((c ^ (((t >> 1) & 1) | (((t >> 3) & 3) << 1))) << 4)), dstv = (unsigned)(t * 128 + ((c ^ ((t >> 1) & 7)) << 4));
;           u32x4 kv[9], vv[9];
; #pragma unroll
;           for (int j = 0; j < 9; ++j) { const int srow = min(R0 + j, 31);
;               kv[j] = *(const u32x4*)(KH + ((size_t)(b * 8 + h) * SEQ + srow * 64 + t) * 64 + c * 8);
;               vv[j] = *(const u32x4*)(VTA + ((size_t)((b * 8 + h) * 32 + srow) * 64 + t) * 64 + c * 8); }
;     ...
;         f32x4 s[8][2];
; #pragma unroll
;         for (int i = 0; i < 8; ++i)
; #pragma unroll
;             for (int t = 0; t < 2; ++t) { const int tok = kc0 + kperm + 4 * t; const LAS unsigned char* kr = Ks + (j0 + i) * 8192 + tok * 128;
;                 const int fk = ((tok >> 1) & 1) | (((tok >> 3) & 3) << 1);
;                 const bf16x8 k0 = *(const LAS bf16x8*)(kr + ((fq ^ fk) << 4)), k1 = *(const LAS bf16x8*)(kr + (((4 + fq) ^ fk) << 4));
;                 f32x4 a = (f32x4){0.f, 0.f, 0.f, 0.f};
;                 a = __builtin_amdgcn_mfma_f32_16x16x32_bf16(k0, qf0, a, 0, 0, 0); a = __builtin_amdgcn_mfma_f32_16x16x32_bf16(k1, qf1, a, 0, 0, 0); s[i][t] = a; }
.Lattn_pf_b:
	s_or_b64 exec, exec, s[98:99]
	v_min_u32_e32 v232, 0x3ff, v244
	v_mov_b32_e32 v229, 0
	v_lshrrev_b32_e32 v233, 4, v232
	v_and_b32_e32 v234, 15, v232
	v_lshlrev_b32_e32 v234, 1, v234
	v_sub_u32_e64 v235, v234, 4 clamp
	v_min_u32_e32 v235, 24, v235
	v_add_u32_e32 v236, s10, v234
	v_lshlrev_b32_e32 v228, 11, v233
	v_lshl_add_u32 v228, v236, 6, v228
	v_add_u32_e32 v228, v228, v28
	v_lshlrev_b32_e32 v228, 7, v228
	v_lshl_add_u64 v[226:227], v[32:33], 0, v[228:229]
	global_load_dwordx4 v[212:215], v[226:227], off
	global_load_dwordx4 v[216:219], v[226:227], off offset:64
	v_and_b32_e32 v236, 7, v233
	v_mul_u32_u24_e32 v236, 0x1d1, v236
	v_add_lshl_u32 v236, v236, v170, 2
	s_mov_b64 exec, s[0:1]
	global_load_dword v220, v236, s[50:51]
	s_mov_b64 exec, -1
	v_cmp_ne_u32_e32 vcc, 24, v235
	v_lshlrev_b32_e32 v228, 18, v233
	v_lshl_add_u32 v228, v235, 13, v228
	v_mov_b32_e32 v231, 0x2000
	v_lshl_add_u32 v238, v128, 7, v228
	v_mov_b32_e32 v239, 0
	v_cndmask_b32_e32 v230, v229, v231, vcc
	v_mov_b32_e32 v231, 0
	v_lshl_add_u64 v[222:223], v[34:35], 0, v[238:239]
	v_lshl_add_u64 v[224:225], v[36:37], 0, v[228:229]
	s_mov_b64 s[98:99], 0x2000
	global_load_dwordx4 v[134:137], v[222:223], off
	global_load_dwordx4 v[138:141], v[224:225], off
	v_lshl_add_u64 v[222:223], v[222:223], 0, s[98:99]
	v_lshl_add_u64 v[224:225], v[224:225], 0, s[98:99]
	global_load_dwordx4 v[142:145], v[222:223], off
	global_load_dwordx4 v[146:149], v[224:225], off
	v_lshl_add_u64 v[222:223], v[222:223], 0, s[98:99]
	v_lshl_add_u64 v[224:225], v[224:225], 0, s[98:99]
	global_load_dwordx4 v[150:153], v[222:223], off
	global_load_dwordx4 v[154:157], v[224:225], off
	v_lshl_add_u64 v[222:223], v[222:223], 0, s[98:99]
	v_lshl_add_u64 v[224:225], v[224:225], 0, s[98:99]
	global_load_dwordx4 v[158:161], v[222:223], off
	global_load_dwordx4 v[162:165], v[224:225], off
	v_lshl_add_u64 v[222:223], v[222:223], 0, s[98:99]
	v_lshl_add_u64 v[224:225], v[224:225], 0, s[98:99]
	global_load_dwordx4 v[166:169], v[222:223], off
	global_load_dwordx4 v[176:179], v[224:225], off
	v_lshl_add_u64 v[222:223], v[222:223], 0, s[98:99]
	v_lshl_add_u64 v[224:225], v[224:225], 0, s[98:99]
	global_load_dwordx4 v[180:183], v[222:223], off
	global_load_dwordx4 v[184:187], v[224:225], off
	v_lshl_add_u64 v[222:223], v[222:223], 0, s[98:99]
	v_lshl_add_u64 v[224:225], v[224:225], 0, s[98:99]
	global_load_dwordx4 v[188:191], v[222:223], off
	global_load_dwordx4 v[192:195], v[224:225], off
	v_lshl_add_u64 v[222:223], v[222:223], 0, s[98:99]
	v_lshl_add_u64 v[224:225], v[224:225], 0, s[98:99]
	global_load_dwordx4 v[196:199], v[222:223], off
	global_load_dwordx4 v[200:203], v[224:225], off
	v_lshl_add_u64 v[222:223], v[222:223], 0, v[230:231]
	v_lshl_add_u64 v[224:225], v[224:225], 0, v[230:231]
	global_load_dwordx4 v[204:207], v[222:223], off
	global_load_dwordx4 v[208:211], v[224:225], off
	ds_read_b128 v[0:3], v63
	v_add_u32_e32 v112, v8, v40
	ds_read_b128 v[8:11], v63 offset:512
	s_waitcnt lgkmcnt(1)
	v_mfma_f32_16x16x32_bf16 v[0:3], v[0:3], v[12:15], 0
	ds_read_b128 v[16:19], v112
	ds_read_b128 v[20:23], v112 offset:512
	s_waitcnt lgkmcnt(1)
	v_mfma_f32_16x16x32_bf16 v[64:67], v[16:19], v[4:7], v[0:3]
	v_mfma_f32_16x16x32_bf16 v[0:3], v[8:11], v[12:15], 0
	s_waitcnt lgkmcnt(0)
	v_mfma_f32_16x16x32_bf16 v[68:71], v[20:23], v[4:7], v[0:3]
	s_nop 5
	ds_read_b128 v[0:3], v63 offset:8192
	ds_read_b128 v[8:11], v63 offset:8704
	ds_read_b128 v[16:19], v112 offset:8192
	ds_read_b128 v[20:23], v112 offset:8704
	s_waitcnt lgkmcnt(3)
	v_mfma_f32_16x16x32_bf16 v[0:3], v[0:3], v[12:15], 0
	s_waitcnt lgkmcnt(1)
	v_mfma_f32_16x16x32_bf16 v[72:75], v[16:19], v[4:7], v[0:3]
	v_mfma_f32_16x16x32_bf16 v[0:3], v[8:11], v[12:15], 0
	s_waitcnt lgkmcnt(0)
	v_mfma_f32_16x16x32_bf16 v[76:79], v[20:23], v[4:7], v[0:3]
	s_nop 5
	ds_read_b128 v[0:3], v63 offset:16384
	ds_read_b128 v[8:11], v63 offset:16896
	ds_read_b128 v[16:19], v112 offset:16384
	ds_read_b128 v[20:23], v112 offset:16896
	s_waitcnt lgkmcnt(3)
	v_mfma_f32_16x16x32_bf16 v[0:3], v[0:3], v[12:15], 0
	s_waitcnt lgkmcnt(1)
	v_mfma_f32_16x16x32_bf16 v[80:83], v[16:19], v[4:7], v[0:3]
	v_mfma_f32_16x16x32_bf16 v[0:3], v[8:11], v[12:15], 0
	s_waitcnt lgkmcnt(0)
	v_mfma_f32_16x16x32_bf16 v[84:87], v[20:23], v[4:7], v[0:3]
	s_nop 5
	ds_read_b128 v[0:3], v63 offset:24576
	ds_read_b128 v[8:11], v63 offset:25088
	ds_read_b128 v[16:19], v112 offset:24576
	ds_read_b128 v[20:23], v112 offset:25088
	s_waitcnt lgkmcnt(3)
	v_mfma_f32_16x16x32_bf16 v[0:3], v[0:3], v[12:15], 0
	s_waitcnt lgkmcnt(1)
	v_mfma_f32_16x16x32_bf16 v[88:91], v[16:19], v[4:7], v[0:3]
	v_mfma_f32_16x16x32_bf16 v[0:3], v[8:11], v[12:15], 0
	s_waitcnt lgkmcnt(0)
	v_mfma_f32_16x16x32_bf16 v[92:95], v[20:23], v[4:7], v[0:3]
	s_nop 5
	ds_read_b128 v[0:3], v63 offset:32768
	ds_read_b128 v[8:11], v63 offset:33280
	ds_read_b128 v[16:19], v112 offset:32768
	ds_read_b128 v[20:23], v112 offset:33280
	s_waitcnt lgkmcnt(3)
	v_mfma_f32_16x16x32_bf16 v[0:3], v[0:3], v[12:15], 0
	s_waitcnt lgkmcnt(1)
	v_mfma_f32_16x16x32_bf16 v[96:99], v[16:19], v[4:7], v[0:3]
	v_mfma_f32_16x16x32_bf16 v[0:3], v[8:11], v[12:15], 0
	s_waitcnt lgkmcnt(0)
	v_mfma_f32_16x16x32_bf16 v[100:103], v[20:23], v[4:7], v[0:3]
	s_nop 5
	ds_read_b128 v[0:3], v63 offset:40960
	ds_read_b128 v[8:11], v63 offset:41472
	ds_read_b128 v[16:19], v112 offset:40960
	ds_read_b128 v[20:23], v112 offset:41472
	s_waitcnt lgkmcnt(3)
	v_mfma_f32_16x16x32_bf16 v[0:3], v[0:3], v[12:15], 0
	s_waitcnt lgkmcnt(1)
	v_mfma_f32_16x16x32_bf16 v[24:27], v[16:19], v[4:7], v[0:3]
	v_mfma_f32_16x16x32_bf16 v[0:3], v[8:11], v[12:15], 0
	s_waitcnt lgkmcnt(0)
; #define LAS __attribute__((address_space(3)))
; __device__ __forceinline__ void attn_phase(const Params& p, LAS unsigned char* lds) {
;     ...
;             for (int t = 0; t < 2; ++t) { const int tok = kc0 + kperm + 4 * t; const LAS unsigned char* kr = Ks + (j0 + i) * 8192 + tok * 128;
;                 const int fk = ((tok >> 1) & 1) | (((tok >> 3) & 3) << 1);
;                 const bf16x8 k0 = *(const LAS bf16x8*)(kr + ((fq ^ fk) << 4)), k1 = *(const LAS bf16x8*)(kr + (((4 + fq) ^ fk) << 4));
;                 f32x4 a = (f32x4){0.f, 0.f, 0.f, 0.f};
;                 a = __builtin_amdgcn_mfma_f32_16x16x32_bf16(k0, qf0, a, 0, 0, 0); a = __builtin_amdgcn_mfma_f32_16x16x32_bf16(k1, qf1, a, 0, 0, 0); s[i][t] = a; }
;         const int qc = q0 + fr, cs0 = min(max(qc - 8, 0), 48);
;         float madd[2][4]; int dco[2][4];
; #pragma unroll
;         for (int t = 0; t < 2; ++t)
; #pragma unroll
;             for (int j = 0; j < 4; ++j) { const int kc = kc0 + 8 * fq + 4 * t + j; madd[t][j] = ((kc >= cs0) && (kc < cs0 + 16)) ? 0.f : -1e30f; dco[t][j] = min(max(kc - qc, -15), 15); }
;         float mx = -1e30f;
; #pragma unroll
;         for (int i = 0; i < 8; ++i) { const int dr = rs + i - r; const LAS float* rrow = rp + (dr + 7) * 31 + 15;
; #pragma unroll
;             for (int t = 0; t < 2; ++t)
; #pragma unroll
;                 for (int j = 0; j < 4; ++j) { const float v = (s[i][t][j] * sc2 + rrow[dco[t][j]]) + madd[t][j]; s[i][t][j] = v; mx = fmaxf(mx, v); } }
	v_mfma_f32_16x16x32_bf16 v[20:23], v[20:23], v[4:7], v[0:3]
	s_nop 5
	ds_read_b128 v[0:3], v63 offset:49152
	ds_read_b128 v[8:11], v63 offset:49664
	ds_read_b128 v[16:19], v112 offset:49152
	ds_read_b128 v[104:107], v112 offset:49664
	s_waitcnt lgkmcnt(3)
	v_mfma_f32_16x16x32_bf16 v[0:3], v[0:3], v[12:15], 0
	s_waitcnt lgkmcnt(1)
	v_mfma_f32_16x16x32_bf16 v[16:19], v[16:19], v[4:7], v[0:3]
	v_mfma_f32_16x16x32_bf16 v[0:3], v[8:11], v[12:15], 0
	s_waitcnt lgkmcnt(0)
	v_mfma_f32_16x16x32_bf16 v[8:11], v[104:107], v[4:7], v[0:3]
	s_nop 5
	ds_read_b128 v[0:3], v63 offset:57344
	ds_read_b128 v[104:107], v63 offset:57856
	ds_read_b128 v[108:111], v112 offset:57344
	ds_read_b128 v[112:115], v112 offset:57856
	v_lshl_add_u32 v63, v46, 2, s20
	s_waitcnt lgkmcnt(3)
	v_mfma_f32_16x16x32_bf16 v[0:3], v[0:3], v[12:15], 0
	s_waitcnt lgkmcnt(1)
	v_mfma_f32_16x16x32_bf16 v[0:3], v[108:111], v[4:7], v[0:3]
	v_lshl_add_u32 v110, v48, 2, s20
	v_lshl_add_u32 v111, v52, 2, s20
	v_mfma_f32_16x16x32_bf16 v[12:15], v[104:107], v[12:15], 0
	v_add_u32_e32 v104, 0x200, v63
	v_add_u32_e32 v106, 0x200, v110
	ds_read2_b32 v[104:105], v104 offset0:104 offset1:135
	ds_read2_b32 v[106:107], v106 offset0:104 offset1:135
	s_waitcnt lgkmcnt(2)
	v_mfma_f32_16x16x32_bf16 v[4:7], v[112:115], v[4:7], v[12:15]
	v_lshl_add_u32 v114, v54, 2, s20
	v_lshl_add_u32 v115, v56, 2, s20
	s_waitcnt lgkmcnt(1)
	v_fmac_f32_e32 v105, 0x3e38aa3b, v72
	v_fmamk_f32 v12, v64, 0x3e38aa3b, v104
	s_waitcnt lgkmcnt(0)
	v_fmamk_f32 v64, v65, 0x3e38aa3b, v106
	v_lshl_add_u32 v106, v50, 2, s20
	v_add_f32_e32 v104, v45, v12
	v_add_u32_e32 v12, 0x200, v106
	ds_read2_b32 v[12:13], v12 offset0:104 offset1:135
	v_add_u32_e32 v14, 0x200, v111
	ds_read2_b32 v[14:15], v14 offset0:104 offset1:135
	v_add_f32_e32 v112, v47, v64
	v_max3_f32 v108, v104, s11, v112
	s_waitcnt lgkmcnt(1)
	v_fmamk_f32 v12, v66, 0x3e38aa3b, v12
	v_add_f32_e32 v113, v49, v12
	s_waitcnt lgkmcnt(0)
	v_fmamk_f32 v12, v67, 0x3e38aa3b, v14
	v_add_u32_e32 v14, 0x200, v114
	ds_read2_b32 v[64:65], v14 offset0:104 offset1:135
	v_add_u32_e32 v14, 0x200, v115
	ds_read2_b32 v[66:67], v14 offset0:104 offset1:135
	v_add_f32_e32 v116, v51, v12
	v_max3_f32 v12, v108, v113, v116
	s_waitcnt lgkmcnt(1)
	v_fmamk_f32 v14, v68, 0x3e38aa3b, v64
	v_add_u32_e32 v64, 0x200, v118
	v_add_f32_e32 v117, v53, v14
	s_waitcnt lgkmcnt(0)
	v_fmamk_f32 v14, v69, 0x3e38aa3b, v66
	ds_read2_b32 v[68:69], v64 offset0:104 offset1:135
	v_add_u32_e32 v64, 0x200, v119
	ds_read2_b32 v[108:109], v64 offset0:104 offset1:135
	v_add_f32_e32 v120, v55, v14
	v_max3_f32 v12, v12, v117, v120
	s_waitcnt lgkmcnt(1)
	v_fmamk_f32 v14, v70, 0x3e38aa3b, v68
	v_add_f32_e32 v121, v57, v14
	s_waitcnt lgkmcnt(0)
	v_fmamk_f32 v14, v71, 0x3e38aa3b, v108
	v_add_f32_e32 v108, v59, v14
	v_fmac_f32_e32 v107, 0x3e38aa3b, v73
	v_max3_f32 v12, v12, v121, v108
	v_add_f32_e32 v105, v45, v105
	v_add_f32_e32 v107, v47, v107
	v_fmac_f32_e32 v13, 0x3e38aa3b, v74
	v_fmac_f32_e32 v15, 0x3e38aa3b, v75
	v_max3_f32 v12, v12, v105, v107
	v_add_f32_e32 v122, v49, v13
	v_add_f32_e32 v123, v51, v15
	v_fmac_f32_e32 v65, 0x3e38aa3b, v76
	v_fmac_f32_e32 v67, 0x3e38aa3b, v77
	v_max3_f32 v12, v12, v122, v123
	v_add_f32_e32 v76, v53, v65
	v_add_f32_e32 v77, v55, v67
	v_add_u32_e32 v63, 0x400, v63
	v_max3_f32 v64, v12, v76, v77
	v_fmac_f32_e32 v109, 0x3e38aa3b, v79
	ds_read2_b32 v[12:13], v63 offset0:38 offset1:69
	v_add_u32_e32 v79, 0x400, v110
	ds_read2_b32 v[14:15], v79 offset0:38 offset1:69
	v_fmac_f32_e32 v69, 0x3e38aa3b, v78
	v_add_f32_e32 v78, v57, v69
	s_waitcnt lgkmcnt(1)
	v_fmamk_f32 v12, v80, 0x3e38aa3b, v12
	v_add_f32_e32 v109, v59, v109
	v_add_f32_e32 v80, v45, v12
	s_waitcnt lgkmcnt(0)
	v_fmamk_f32 v12, v81, 0x3e38aa3b, v14
	v_add_u32_e32 v81, 0x400, v106
	v_max3_f32 v68, v64, v78, v109
	ds_read2_b32 v[64:65], v81 offset0:38 offset1:69
	v_add_u32_e32 v106, 0x400, v111
	ds_read2_b32 v[66:67], v106 offset0:38 offset1:69
	v_add_f32_e32 v110, v47, v12
	v_max3_f32 v12, v68, v80, v110
	s_waitcnt lgkmcnt(1)
	v_fmamk_f32 v14, v82, 0x3e38aa3b, v64
	v_add_f32_e32 v82, v49, v14
	s_waitcnt lgkmcnt(0)
	v_fmamk_f32 v14, v83, 0x3e38aa3b, v66
	v_add_u32_e32 v83, 0x400, v114
	ds_read2_b32 v[68:69], v83 offset0:38 offset1:69
	v_add_u32_e32 v111, 0x400, v115
	ds_read2_b32 v[70:71], v111 offset0:38 offset1:69
	v_add_f32_e32 v114, v51, v14
	v_add_u32_e32 v115, 0x400, v119
	s_waitcnt lgkmcnt(1)
	v_fmamk_f32 v14, v84, 0x3e38aa3b, v68
	v_add_f32_e32 v84, v53, v14
	s_waitcnt lgkmcnt(0)
	v_fmamk_f32 v14, v85, 0x3e38aa3b, v70
	v_add_u32_e32 v85, 0x400, v118
	ds_read2_b32 v[72:73], v85 offset0:38 offset1:69
	ds_read2_b32 v[74:75], v115 offset0:38 offset1:69
	v_add_f32_e32 v118, v55, v14
	v_max3_f32 v12, v12, v82, v114
	v_max3_f32 v12, v12, v84, v118
	s_waitcnt lgkmcnt(1)
	v_fmamk_f32 v14, v86, 0x3e38aa3b, v72
	v_add_f32_e32 v86, v57, v14
	s_waitcnt lgkmcnt(0)
	v_fmamk_f32 v14, v87, 0x3e38aa3b, v74
	v_add_f32_e32 v87, v59, v14
	v_fmac_f32_e32 v13, 0x3e38aa3b, v88
	v_fmac_f32_e32 v15, 0x3e38aa3b, v89
	v_max3_f32 v12, v12, v86, v87
	v_add_f32_e32 v88, v45, v13
	v_add_f32_e32 v89, v47, v15
	v_fmac_f32_e32 v65, 0x3e38aa3b, v90
	v_fmac_f32_e32 v67, 0x3e38aa3b, v91
	v_max3_f32 v12, v12, v88, v89
	v_add_f32_e32 v90, v49, v65
	v_add_f32_e32 v91, v51, v67
	v_fmac_f32_e32 v69, 0x3e38aa3b, v92
	v_fmac_f32_e32 v71, 0x3e38aa3b, v93
	v_max3_f32 v12, v12, v90, v91
	v_add_f32_e32 v92, v53, v69
	v_add_f32_e32 v93, v55, v71
	v_max3_f32 v64, v12, v92, v93
	ds_read2_b32 v[12:13], v63 offset0:100 offset1:131
	ds_read2_b32 v[14:15], v79 offset0:100 offset1:131
	v_fmac_f32_e32 v73, 0x3e38aa3b, v94
	v_fmac_f32_e32 v75, 0x3e38aa3b, v95
	v_add_f32_e32 v94, v57, v73
	v_add_f32_e32 v95, v59, v75
	s_waitcnt lgkmcnt(1)
; #define LAS __attribute__((address_space(3)))
; __device__ __forceinline__ void attn_phase(const Params& p, LAS unsigned char* lds) {
;     ...
;         for (int i = 0; i < 8; ++i) { const int dr = rs + i - r; const LAS float* rrow = rp + (dr + 7) * 31 + 15;
; #pragma unroll
;             for (int t = 0; t < 2; ++t)
; #pragma unroll
;                 for (int j = 0; j < 4; ++j) { const float v = (s[i][t][j] * sc2 + rrow[dco[t][j]]) + madd[t][j]; s[i][t][j] = v; mx = fmaxf(mx, v); } }
;         mx = fmaxf(mx, __shfl_xor(mx, 16)); mx = fmaxf(mx, __shfl_xor(mx, 32));
;         float sum = 0.f;
; #pragma unroll
;         for (int i = 0; i < 8; ++i)
; #pragma unroll
;             for (int t = 0; t < 2; ++t)
; #pragma unroll
;                 for (int j = 0; j < 4; ++j) { const float e = __builtin_amdgcn_exp2f(s[i][t][j] - mx); s[i][t][j] = e; sum += e; }
;         sum += __shfl_xor(sum, 16); sum += __shfl_xor(sum, 32);
	v_fmamk_f32 v12, v96, 0x3e38aa3b, v12
	v_max3_f32 v68, v64, v94, v95
	v_add_f32_e32 v96, v45, v12
	ds_read2_b32 v[64:65], v81 offset0:100 offset1:131
	s_waitcnt lgkmcnt(1)
	v_fmamk_f32 v12, v97, 0x3e38aa3b, v14
	v_add_f32_e32 v97, v47, v12
	ds_read2_b32 v[66:67], v106 offset0:100 offset1:131
	v_max3_f32 v12, v68, v96, v97
	ds_read2_b32 v[68:69], v83 offset0:100 offset1:131
	ds_read2_b32 v[70:71], v111 offset0:100 offset1:131
	ds_read2_b32 v[72:73], v85 offset0:100 offset1:131
	s_waitcnt lgkmcnt(4)
	v_fmamk_f32 v14, v98, 0x3e38aa3b, v64
	ds_read2_b32 v[74:75], v115 offset0:100 offset1:131
	v_add_f32_e32 v64, v49, v14
	s_waitcnt lgkmcnt(4)
	v_fmamk_f32 v14, v99, 0x3e38aa3b, v66
	v_add_f32_e32 v66, v51, v14
	s_waitcnt lgkmcnt(3)
	v_fmamk_f32 v14, v100, 0x3e38aa3b, v68
	v_add_f32_e32 v68, v53, v14
	s_waitcnt lgkmcnt(2)
	v_fmamk_f32 v14, v101, 0x3e38aa3b, v70
	v_add_f32_e32 v70, v55, v14
	s_waitcnt lgkmcnt(1)
	v_fmamk_f32 v14, v102, 0x3e38aa3b, v72
	v_max3_f32 v12, v12, v64, v66
	v_add_f32_e32 v72, v57, v14
	s_waitcnt lgkmcnt(0)
	v_fmamk_f32 v14, v103, 0x3e38aa3b, v74
	v_max3_f32 v12, v12, v68, v70
	v_add_f32_e32 v74, v59, v14
	v_fmac_f32_e32 v13, 0x3e38aa3b, v24
	v_fmac_f32_e32 v15, 0x3e38aa3b, v25
	v_max3_f32 v12, v12, v72, v74
	v_add_f32_e32 v98, v45, v13
	v_add_f32_e32 v99, v47, v15
	v_fmac_f32_e32 v65, 0x3e38aa3b, v26
	v_fmac_f32_e32 v67, 0x3e38aa3b, v27
	v_max3_f32 v12, v12, v98, v99
	v_add_f32_e32 v26, v49, v65
	v_add_f32_e32 v27, v51, v67
	v_fmac_f32_e32 v69, 0x3e38aa3b, v20
	v_fmac_f32_e32 v71, 0x3e38aa3b, v21
	v_max3_f32 v12, v12, v26, v27
	v_add_f32_e32 v65, v53, v69
	v_add_f32_e32 v67, v55, v71
	v_max3_f32 v20, v12, v65, v67
	ds_read2_b32 v[12:13], v63 offset0:162 offset1:193
	ds_read2_b32 v[14:15], v79 offset0:162 offset1:193
	v_fmac_f32_e32 v73, 0x3e38aa3b, v22
	v_fmac_f32_e32 v75, 0x3e38aa3b, v23
	v_add_f32_e32 v69, v57, v73
	v_add_f32_e32 v63, v59, v75
	v_max3_f32 v22, v20, v69, v63
	ds_read2_b32 v[20:21], v81 offset0:162 offset1:193
	s_waitcnt lgkmcnt(2)
	v_fmamk_f32 v12, v16, 0x3e38aa3b, v12
	s_waitcnt lgkmcnt(1)
	v_fmamk_f32 v14, v17, 0x3e38aa3b, v14
	ds_read2_b32 v[16:17], v106 offset0:162 offset1:193
	v_add_f32_e32 v12, v45, v12
	v_add_f32_e32 v71, v47, v14
	v_max3_f32 v14, v22, v12, v71
	s_waitcnt lgkmcnt(1)
	v_fmamk_f32 v18, v18, 0x3e38aa3b, v20
	ds_read2_b32 v[22:23], v83 offset0:162 offset1:193
	v_add_f32_e32 v73, v49, v18
	s_waitcnt lgkmcnt(1)
	v_fmamk_f32 v16, v19, 0x3e38aa3b, v16
	ds_read2_b32 v[18:19], v111 offset0:162 offset1:193
	v_add_f32_e32 v75, v51, v16
	s_waitcnt lgkmcnt(1)
	v_fmamk_f32 v8, v8, 0x3e38aa3b, v22
	v_add_f32_e32 v79, v53, v8
	ds_read2_b32 v[24:25], v85 offset0:162 offset1:193
	s_waitcnt lgkmcnt(1)
	v_fmamk_f32 v16, v9, 0x3e38aa3b, v18
	ds_read2_b32 v[8:9], v115 offset0:162 offset1:193
	v_max3_f32 v14, v14, v73, v75
	v_add_f32_e32 v81, v55, v16
	s_waitcnt lgkmcnt(1)
	v_fmamk_f32 v10, v10, 0x3e38aa3b, v24
	v_max3_f32 v14, v14, v79, v81
	s_waitcnt lgkmcnt(0)
	v_fmamk_f32 v8, v11, 0x3e38aa3b, v8
	v_add_f32_e32 v83, v57, v10
	v_add_f32_e32 v85, v59, v8
	v_fmac_f32_e32 v13, 0x3e38aa3b, v0
	v_fmac_f32_e32 v15, 0x3e38aa3b, v1
	v_max3_f32 v8, v14, v83, v85
	v_add_f32_e32 v100, v45, v13
	v_add_f32_e32 v101, v47, v15
	v_fmac_f32_e32 v21, 0x3e38aa3b, v2
	v_fmac_f32_e32 v17, 0x3e38aa3b, v3
	v_and_b32_e32 v2, 64, v62
	v_max3_f32 v0, v8, v100, v101
	v_add_f32_e32 v102, v49, v21
	v_add_f32_e32 v103, v51, v17
	v_fmac_f32_e32 v23, 0x3e38aa3b, v4
	v_fmac_f32_e32 v19, 0x3e38aa3b, v5
	v_xor_b32_e32 v1, 16, v62
	v_add_u32_e32 v2, 64, v2
	v_max3_f32 v0, v0, v102, v103
	v_add_f32_e32 v106, v53, v23
	v_add_f32_e32 v111, v55, v19
	v_fmac_f32_e32 v25, 0x3e38aa3b, v6
	v_fmac_f32_e32 v9, 0x3e38aa3b, v7
	v_cmp_lt_i32_e32 vcc, v1, v2
	v_max3_f32 v0, v0, v106, v111
	v_add_f32_e32 v115, v57, v25
	v_add_f32_e32 v119, v59, v9
	v_cndmask_b32_e32 v1, v62, v1, vcc
	v_max3_f32 v0, v0, v115, v119
	v_lshlrev_b32_e32 v16, 2, v1
	ds_bpermute_b32 v1, v16, v0
	s_waitcnt lgkmcnt(0)
	v_max_f32_e32 v1, v1, v1
	v_max_f32_e32 v0, v0, v1
	v_xor_b32_e32 v1, 32, v62
	v_cmp_lt_i32_e32 vcc, v1, v2
	s_nop 1
	v_cndmask_b32_e32 v1, v62, v1, vcc
	v_lshlrev_b32_e32 v17, 2, v1
	ds_bpermute_b32 v1, v17, v0
	s_waitcnt lgkmcnt(0)
	v_max_f32_e32 v1, v1, v1
	v_max_f32_e32 v124, v0, v1
	v_sub_f32_e32 v0, v104, v124
	v_exp_f32_e32 v0, v0
	v_sub_f32_e32 v1, v112, v124
	v_exp_f32_e32 v1, v1
	v_sub_f32_e32 v2, v113, v124
	v_exp_f32_e32 v2, v2
	v_sub_f32_e32 v3, v116, v124
	v_exp_f32_e32 v3, v3
	v_sub_f32_e32 v5, v117, v124
	v_add_f32_e32 v4, 0, v0
	v_exp_f32_e32 v5, v5
	v_sub_f32_e32 v6, v120, v124
	v_add_f32_e32 v4, v1, v4
	v_exp_f32_e32 v6, v6
	v_sub_f32_e32 v7, v121, v124
	v_add_f32_e32 v4, v2, v4
	v_exp_f32_e32 v7, v7
	v_sub_f32_e32 v8, v108, v124
	v_add_f32_e32 v4, v3, v4
	v_exp_f32_e32 v8, v8
	v_sub_f32_e32 v9, v105, v124
	v_add_f32_e32 v4, v5, v4
	v_exp_f32_e32 v22, v9
	v_sub_f32_e32 v9, v107, v124
	v_add_f32_e32 v4, v6, v4
	v_exp_f32_e32 v23, v9
	v_sub_f32_e32 v9, v122, v124
	v_add_f32_e32 v4, v7, v4
	v_exp_f32_e32 v24, v9
	v_sub_f32_e32 v9, v123, v124
	v_add_f32_e32 v4, v8, v4
	v_exp_f32_e32 v25, v9
	v_sub_f32_e32 v9, v76, v124
	v_add_f32_e32 v4, v22, v4
	v_exp_f32_e32 v76, v9
	v_sub_f32_e32 v9, v77, v124
	v_add_f32_e32 v4, v23, v4
	v_exp_f32_e32 v77, v9
	v_sub_f32_e32 v9, v78, v124
	v_add_f32_e32 v4, v24, v4
	v_exp_f32_e32 v78, v9
	v_sub_f32_e32 v9, v109, v124
	v_add_f32_e32 v4, v25, v4
	v_exp_f32_e32 v104, v9
	v_sub_f32_e32 v9, v80, v124
	v_add_f32_e32 v4, v76, v4
	v_exp_f32_e32 v80, v9
	v_sub_f32_e32 v9, v110, v124
	v_add_f32_e32 v4, v77, v4
	v_exp_f32_e32 v105, v9
	v_sub_f32_e32 v9, v82, v124
	v_add_f32_e32 v4, v78, v4
	v_exp_f32_e32 v82, v9
; #define LAS __attribute__((address_space(3)))
; __device__ __forceinline__ unsigned cvt_pk_bf16(float lo, float hi) { unsigned r; asm volatile("v_cvt_pk_bf16_f32 %0, %1, %2" : "=v"(r) : "v"(lo), "v"(hi)); return r; }
; __device__ __forceinline__ void attn_phase(const Params& p, LAS unsigned char* lds) {
;     ...
;         float sum = 0.f;
; #pragma unroll
;         for (int i = 0; i < 8; ++i)
; #pragma unroll
;             for (int t = 0; t < 2; ++t)
; #pragma unroll
;                 for (int j = 0; j < 4; ++j) { const float e = __builtin_amdgcn_exp2f(s[i][t][j] - mx); s[i][t][j] = e; sum += e; }
;         sum += __shfl_xor(sum, 16); sum += __shfl_xor(sum, 32);
;         const float inv = 1.0f / sum;
;         f32x4 o[4];
; #pragma unroll
;         for (int nb = 0; nb < 4; ++nb) o[nb] = (f32x4){0.f, 0.f, 0.f, 0.f};
;         const int vc = (kc0 >> 3) + fq;
; #pragma unroll
;         for (int i = 0; i < 8; ++i) {
;             u32x4 pw; pw.x = cvt_pk_bf16(s[i][0][0], s[i][0][1]); pw.y = cvt_pk_bf16(s[i][0][2], s[i][0][3]); pw.z = cvt_pk_bf16(s[i][1][0], s[i][1][1]); pw.w = cvt_pk_bf16(s[i][1][2], s[i][1][3]);
;             const bf16x8 pf = __builtin_bit_cast(bf16x8, pw);
; #pragma unroll
;             for (int nb = 0; nb < 4; ++nb) { const int d = nb * 16 + fr; const bf16x8 va = *(const LAS bf16x8*)(Vs + (j0 + i) * 8192 + d * 128 + ((vc ^ ((d >> 1) & 7)) << 4));
;                 o[nb] = __builtin_amdgcn_mfma_f32_16x16x32_bf16(va, pf, o[nb], 0, 0, 0); } }
	v_sub_f32_e32 v9, v114, v124
	v_add_f32_e32 v4, v104, v4
	v_exp_f32_e32 v107, v9
	v_sub_f32_e32 v9, v84, v124
	v_add_f32_e32 v4, v80, v4
	v_exp_f32_e32 v84, v9
	v_sub_f32_e32 v9, v118, v124
	v_add_f32_e32 v4, v105, v4
	v_exp_f32_e32 v108, v9
	v_sub_f32_e32 v9, v86, v124
	v_add_f32_e32 v4, v82, v4
	v_exp_f32_e32 v86, v9
	v_sub_f32_e32 v9, v87, v124
	v_add_f32_e32 v4, v107, v4
	v_exp_f32_e32 v87, v9
	v_sub_f32_e32 v9, v88, v124
	v_add_f32_e32 v4, v84, v4
	v_exp_f32_e32 v88, v9
	v_sub_f32_e32 v9, v89, v124
	v_add_f32_e32 v4, v108, v4
	v_exp_f32_e32 v89, v9
	v_sub_f32_e32 v9, v90, v124
	v_add_f32_e32 v4, v86, v4
	v_exp_f32_e32 v90, v9
	v_sub_f32_e32 v9, v91, v124
	v_add_f32_e32 v4, v87, v4
	v_exp_f32_e32 v91, v9
	v_sub_f32_e32 v9, v92, v124
	v_add_f32_e32 v4, v88, v4
	v_exp_f32_e32 v92, v9
	v_sub_f32_e32 v9, v93, v124
	v_add_f32_e32 v4, v89, v4
	v_exp_f32_e32 v93, v9
	v_sub_f32_e32 v9, v94, v124
	v_add_f32_e32 v4, v90, v4
	v_exp_f32_e32 v94, v9
	v_sub_f32_e32 v9, v95, v124
	v_add_f32_e32 v4, v91, v4
	v_exp_f32_e32 v95, v9
	v_sub_f32_e32 v9, v96, v124
	v_add_f32_e32 v4, v92, v4
	v_exp_f32_e32 v96, v9
	v_sub_f32_e32 v9, v97, v124
	v_add_f32_e32 v4, v93, v4
	v_exp_f32_e32 v97, v9
	v_sub_f32_e32 v9, v64, v124
	v_add_f32_e32 v4, v94, v4
	v_exp_f32_e32 v109, v9
	v_sub_f32_e32 v9, v66, v124
	v_add_f32_e32 v4, v95, v4
	v_exp_f32_e32 v110, v9
	v_sub_f32_e32 v9, v68, v124
	v_add_f32_e32 v4, v96, v4
	v_exp_f32_e32 v112, v9
	v_sub_f32_e32 v9, v70, v124
	v_add_f32_e32 v4, v97, v4
	v_exp_f32_e32 v113, v9
	v_sub_f32_e32 v9, v72, v124
	v_add_f32_e32 v4, v109, v4
	v_exp_f32_e32 v114, v9
	v_sub_f32_e32 v9, v74, v124
	v_add_f32_e32 v4, v110, v4
	v_exp_f32_e32 v116, v9
	v_sub_f32_e32 v9, v98, v124
	v_add_f32_e32 v4, v112, v4
	v_exp_f32_e32 v98, v9
	v_sub_f32_e32 v9, v99, v124
	v_add_f32_e32 v4, v113, v4
	v_exp_f32_e32 v99, v9
	v_sub_f32_e32 v9, v26, v124
	v_add_f32_e32 v4, v114, v4
	v_exp_f32_e32 v26, v9
	v_sub_f32_e32 v9, v27, v124
	v_add_f32_e32 v4, v116, v4
	v_exp_f32_e32 v27, v9
	v_add_f32_e32 v4, v98, v4
	v_add_f32_e32 v4, v99, v4
	v_add_f32_e32 v4, v26, v4
	v_add_f32_e32 v13, v27, v4
	v_sub_f32_e32 v4, v65, v124
	v_exp_f32_e32 v117, v4
	v_sub_f32_e32 v4, v67, v124
	v_exp_f32_e32 v118, v4
	v_sub_f32_e32 v9, v69, v124
	v_cvt_pk_bf16_f32 v0, v0, v1
	v_cvt_pk_bf16_f32 v1, v2, v3
	v_cvt_pk_bf16_f32 v2, v5, v6
	v_cvt_pk_bf16_f32 v3, v7, v8
	v_exp_f32_e32 v121, v9
	v_sub_f32_e32 v8, v63, v124
	v_exp_f32_e32 v63, v8
	v_add_f32_e32 v13, v117, v13
	v_add_f32_e32 v13, v118, v13
	v_add_u32_e32 v120, s16, v41
	v_add_f32_e32 v13, v121, v13
	v_sub_f32_e32 v18, v12, v124
	ds_read_b128 v[4:7], v120
	ds_read_b128 v[8:11], v120 offset:2048
	v_add_f32_e32 v72, v63, v13
	ds_read_b128 v[12:15], v120 offset:4096
	v_exp_f32_e32 v122, v18
	ds_read_b128 v[18:21], v120 offset:6144
	v_sub_f32_e32 v68, v71, v124
	v_cvt_pk_bf16_f32 v22, v22, v23
	v_cvt_pk_bf16_f32 v23, v24, v25
	v_cvt_pk_bf16_f32 v24, v76, v77
	v_exp_f32_e32 v76, v68
	v_cvt_pk_bf16_f32 v25, v78, v104
	ds_read_b128 v[64:67], v120 offset:8192
	ds_read_b128 v[68:71], v120 offset:10240
	s_waitcnt lgkmcnt(5)
	v_mfma_f32_16x16x32_bf16 v[4:7], v[4:7], v[0:3], 0
	v_sub_f32_e32 v104, v75, v124
	s_lshl_b32 s16, s43, 11
	s_add_i32 s44, s44, s16
	s_waitcnt lgkmcnt(4)
	v_mfma_f32_16x16x32_bf16 v[8:11], v[8:11], v[0:3], 0
	s_waitcnt lgkmcnt(3)
	v_mfma_f32_16x16x32_bf16 v[12:15], v[12:15], v[0:3], 0
	s_waitcnt lgkmcnt(2)
	v_mfma_f32_16x16x32_bf16 v[0:3], v[18:21], v[0:3], 0
	v_add_f32_e32 v18, v122, v72
	v_add_f32_e32 v77, v76, v18
	v_sub_f32_e32 v18, v73, v124
	v_exp_f32_e32 v78, v18
	ds_read_b128 v[18:21], v120 offset:12288
	s_waitcnt lgkmcnt(2)
	v_mfma_f32_16x16x32_bf16 v[4:7], v[64:67], v[22:25], v[4:7]
	ds_read_b128 v[64:67], v120 offset:14336
	v_add_f32_e32 v77, v78, v77
	s_waitcnt lgkmcnt(2)
	v_mfma_f32_16x16x32_bf16 v[8:11], v[68:71], v[22:25], v[8:11]
	v_cvt_pk_bf16_f32 v68, v80, v105
	v_cvt_pk_bf16_f32 v69, v82, v107
	v_cvt_pk_bf16_f32 v70, v84, v108
	v_cvt_pk_bf16_f32 v71, v86, v87
	ds_read_b128 v[72:75], v120 offset:16384
	s_waitcnt lgkmcnt(2)
	v_mfma_f32_16x16x32_bf16 v[12:15], v[18:21], v[22:25], v[12:15]
	ds_read_b128 v[18:21], v120 offset:18432
	v_exp_f32_e32 v80, v104
	v_sub_f32_e32 v86, v102, v124
	s_waitcnt lgkmcnt(2)
	v_mfma_f32_16x16x32_bf16 v[0:3], v[64:67], v[22:25], v[0:3]
	v_sub_f32_e32 v22, v79, v124
	v_exp_f32_e32 v79, v22
	ds_read_b128 v[22:25], v120 offset:20480
	s_waitcnt lgkmcnt(1)
	v_mfma_f32_16x16x32_bf16 v[8:11], v[18:21], v[68:71], v[8:11]
	ds_read_b128 v[18:21], v120 offset:22528
	v_sub_f32_e32 v64, v81, v124
	v_exp_f32_e32 v81, v64
	s_waitcnt lgkmcnt(1)
	v_mfma_f32_16x16x32_bf16 v[12:15], v[22:25], v[68:71], v[12:15]
	v_sub_f32_e32 v22, v83, v124
	v_exp_f32_e32 v82, v22
	v_add_f32_e32 v77, v80, v77
	s_waitcnt lgkmcnt(0)
	v_mfma_f32_16x16x32_bf16 v[0:3], v[18:21], v[68:71], v[0:3]
	v_add_f32_e32 v18, v79, v77
	v_cvt_pk_bf16_f32 v64, v88, v89
	v_cvt_pk_bf16_f32 v65, v90, v91
	v_mfma_f32_16x16x32_bf16 v[4:7], v[72:75], v[68:71], v[4:7]
	v_cvt_pk_bf16_f32 v66, v92, v93
	v_cvt_pk_bf16_f32 v67, v94, v95
	ds_read_b128 v[72:75], v120 offset:24576
	ds_read_b128 v[22:25], v120 offset:26624
	v_add_f32_e32 v18, v81, v18
	v_add_f32_e32 v77, v82, v18
	ds_read_b128 v[18:21], v120 offset:28672
	s_waitcnt lgkmcnt(1)
	v_mfma_f32_16x16x32_bf16 v[8:11], v[22:25], v[64:67], v[8:11]
	ds_read_b128 v[22:25], v120 offset:30720
	v_sub_f32_e32 v68, v85, v124
	v_exp_f32_e32 v83, v68
	s_waitcnt lgkmcnt(1)
; #define LAS __attribute__((address_space(3)))
; __device__ __forceinline__ unsigned cvt_pk_bf16(float lo, float hi) { unsigned r; asm volatile("v_cvt_pk_bf16_f32 %0, %1, %2" : "=v"(r) : "v"(lo), "v"(hi)); return r; }
; __device__ __forceinline__ void attn_phase(const Params& p, LAS unsigned char* lds) {
;     ...
;         sum += __shfl_xor(sum, 16); sum += __shfl_xor(sum, 32);
;         const float inv = 1.0f / sum;
;         f32x4 o[4];
; #pragma unroll
;         for (int nb = 0; nb < 4; ++nb) o[nb] = (f32x4){0.f, 0.f, 0.f, 0.f};
;         const int vc = (kc0 >> 3) + fq;
; #pragma unroll
;         for (int i = 0; i < 8; ++i) {
;             u32x4 pw; pw.x = cvt_pk_bf16(s[i][0][0], s[i][0][1]); pw.y = cvt_pk_bf16(s[i][0][2], s[i][0][3]); pw.z = cvt_pk_bf16(s[i][1][0], s[i][1][1]); pw.w = cvt_pk_bf16(s[i][1][2], s[i][1][3]);
;             const bf16x8 pf = __builtin_bit_cast(bf16x8, pw);
; #pragma unroll
;             for (int nb = 0; nb < 4; ++nb) { const int d = nb * 16 + fr; const bf16x8 va = *(const LAS bf16x8*)(Vs + (j0 + i) * 8192 + d * 128 + ((vc ^ ((d >> 1) & 7)) << 4));
;                 o[nb] = __builtin_amdgcn_mfma_f32_16x16x32_bf16(va, pf, o[nb], 0, 0, 0); } }
;         float q2 = 0.f;
; #pragma unroll
;         for (int nb = 0; nb < 4; ++nb) { o[nb] = o[nb] * inv; q2 += (o[nb][0] * o[nb][0] + o[nb][1] * o[nb][1]) + (o[nb][2] * o[nb][2] + o[nb][3] * o[nb][3]); }
;         q2 += __shfl_xor(q2, 16); q2 += __shfl_xor(q2, 32);
;         if (fq == 0) SSQNA[(size_t)tq * 8 + h] = q2;
;         bf16_t* op = YCAT + (size_t)tq * DM + 512 + h * 64 + 4 * fq;
; #pragma unroll
;         for (int nb = 0; nb < 4; ++nb) { u32x2 wv; wv.x = cvt_pk_bf16(o[nb][0], o[nb][1]); wv.y = cvt_pk_bf16(o[nb][2], o[nb][3]); *(u32x2*)(op + nb * 16) = wv; }
;     }
;     __syncthreads();
	v_mfma_f32_16x16x32_bf16 v[12:15], v[18:21], v[64:67], v[12:15]
	v_sub_f32_e32 v18, v100, v124
	v_cvt_pk_bf16_f32 v68, v96, v97
	v_cvt_pk_bf16_f32 v69, v109, v110
	v_mfma_f32_16x16x32_bf16 v[4:7], v[72:75], v[64:67], v[4:7]
	v_cvt_pk_bf16_f32 v70, v112, v113
	v_cvt_pk_bf16_f32 v71, v114, v116
	ds_read_b128 v[72:75], v120 offset:32768
	v_exp_f32_e32 v84, v18
	ds_read_b128 v[18:21], v120 offset:34816
	s_waitcnt lgkmcnt(2)
	v_mfma_f32_16x16x32_bf16 v[0:3], v[22:25], v[64:67], v[0:3]
	v_add_f32_e32 v22, v83, v77
	v_add_f32_e32 v77, v84, v22
	v_sub_f32_e32 v22, v101, v124
	v_exp_f32_e32 v85, v22
	ds_read_b128 v[22:25], v120 offset:36864
	s_waitcnt lgkmcnt(1)
	v_mfma_f32_16x16x32_bf16 v[8:11], v[18:21], v[68:71], v[8:11]
	ds_read_b128 v[18:21], v120 offset:38912
	v_cvt_pk_bf16_f32 v64, v98, v99
	v_cvt_pk_bf16_f32 v65, v26, v27
	v_exp_f32_e32 v26, v86
	v_sub_f32_e32 v27, v103, v124
	v_exp_f32_e32 v27, v27
	s_waitcnt lgkmcnt(0)
	v_mfma_f32_16x16x32_bf16 v[0:3], v[18:21], v[68:71], v[0:3]
	v_add_f32_e32 v18, v85, v77
	v_add_f32_e32 v18, v26, v18
	v_cvt_pk_bf16_f32 v66, v117, v118
	v_mfma_f32_16x16x32_bf16 v[4:7], v[72:75], v[68:71], v[4:7]
	v_cvt_pk_bf16_f32 v67, v121, v63
	ds_read_b128 v[72:75], v120 offset:40960
	v_add_f32_e32 v63, v27, v18
	v_mfma_f32_16x16x32_bf16 v[12:15], v[22:25], v[68:71], v[12:15]
	ds_read_b128 v[22:25], v120 offset:43008
	ds_read_b128 v[18:21], v120 offset:45056
	v_sub_f32_e32 v77, v106, v124
	s_waitcnt lgkmcnt(2)
	v_mfma_f32_16x16x32_bf16 v[4:7], v[72:75], v[64:67], v[4:7]
	s_waitcnt lgkmcnt(1)
	v_mfma_f32_16x16x32_bf16 v[8:11], v[22:25], v[64:67], v[8:11]
	ds_read_b128 v[22:25], v120 offset:47104
	v_cvt_pk_bf16_f32 v68, v122, v76
	v_cvt_pk_bf16_f32 v69, v78, v80
	v_cvt_pk_bf16_f32 v70, v79, v81
	v_cvt_pk_bf16_f32 v71, v82, v83
	ds_read_b128 v[72:75], v120 offset:49152
	s_waitcnt lgkmcnt(2)
	v_mfma_f32_16x16x32_bf16 v[12:15], v[18:21], v[64:67], v[12:15]
	ds_read_b128 v[18:21], v120 offset:51200
	v_exp_f32_e32 v76, v77
	v_sub_f32_e32 v77, v111, v124
	s_waitcnt lgkmcnt(2)
	v_mfma_f32_16x16x32_bf16 v[0:3], v[22:25], v[64:67], v[0:3]
	ds_read_b128 v[22:25], v120 offset:53248
	v_exp_f32_e32 v64, v77
	v_sub_f32_e32 v65, v115, v124
	s_waitcnt lgkmcnt(1)
	v_mfma_f32_16x16x32_bf16 v[8:11], v[18:21], v[68:71], v[8:11]
	v_sub_f32_e32 v18, v119, v124
	v_add_f32_e32 v63, v76, v63
	v_add_f32_e32 v63, v64, v63
	v_mfma_f32_16x16x32_bf16 v[4:7], v[72:75], v[68:71], v[4:7]
	v_exp_f32_e32 v73, v18
	ds_read_b128 v[18:21], v120 offset:55296
	v_exp_f32_e32 v72, v65
	s_waitcnt lgkmcnt(1)
	v_mfma_f32_16x16x32_bf16 v[12:15], v[22:25], v[68:71], v[12:15]
	v_cvt_pk_bf16_f32 v22, v84, v85
	v_cvt_pk_bf16_f32 v23, v26, v27
	v_add_f32_e32 v26, v72, v63
	v_cvt_pk_bf16_f32 v24, v76, v64
	v_cvt_pk_bf16_f32 v25, v72, v73
	ds_read_b128 v[64:67], v120 offset:57344
	v_add_f32_e32 v26, v73, v26
	s_waitcnt lgkmcnt(1)
	v_mfma_f32_16x16x32_bf16 v[0:3], v[18:21], v[68:71], v[0:3]
	ds_read_b128 v[18:21], v120 offset:59392
	ds_bpermute_b32 v27, v16, v26
	ds_read_b128 v[68:71], v120 offset:61440
	s_waitcnt lgkmcnt(2)
	v_mfma_f32_16x16x32_bf16 v[18:21], v[18:21], v[22:25], v[8:11]
	s_waitcnt lgkmcnt(1)
	v_add_f32_e32 v26, v26, v27
	ds_bpermute_b32 v27, v17, v26
	ds_read_b128 v[8:11], v120 offset:63488
	v_mfma_f32_16x16x32_bf16 v[4:7], v[64:67], v[22:25], v[4:7]
	s_waitcnt lgkmcnt(1)
	v_add_f32_e32 v26, v26, v27
	v_div_scale_f32 v27, s[20:21], v26, v26, 1.0
	v_rcp_f32_e32 v63, v27
	v_mfma_f32_16x16x32_bf16 v[12:15], v[68:71], v[22:25], v[12:15]
	s_waitcnt lgkmcnt(0)
	v_mfma_f32_16x16x32_bf16 v[22:25], v[8:11], v[22:25], v[0:3]
	s_nop 2
	v_fma_f32 v0, -v27, v63, 1.0
	v_fmac_f32_e32 v63, v0, v63
	v_div_scale_f32 v0, vcc, 1.0, v26, 1.0
	v_mul_f32_e32 v1, v0, v63
	v_fma_f32 v2, -v27, v1, v0
	v_fmac_f32_e32 v1, v2, v63
	v_fma_f32 v0, -v27, v1, v0
	v_div_fmas_f32 v0, v0, v63, v1
	v_div_fixup_f32 v26, v0, v26, 1.0
	v_pk_mul_f32 v[2:3], v[26:27], v[6:7] op_sel_hi:[0,1]
	v_pk_mul_f32 v[10:11], v[26:27], v[4:5] op_sel_hi:[0,1]
	v_mul_f32_e32 v0, v11, v11
	v_mul_f32_e32 v1, v3, v3
	v_fmac_f32_e32 v0, v10, v10
	v_fmac_f32_e32 v1, v2, v2
	v_add_f32_e32 v4, v0, v1
	v_pk_mul_f32 v[0:1], v[26:27], v[20:21] op_sel_hi:[0,1]
	v_pk_mul_f32 v[6:7], v[26:27], v[18:19] op_sel_hi:[0,1]
	v_mul_f32_e32 v5, v7, v7
	v_mul_f32_e32 v8, v1, v1
	v_fmac_f32_e32 v5, v6, v6
	v_fmac_f32_e32 v8, v0, v0
	v_add_f32_e32 v5, v5, v8
	v_add_f32_e32 v8, v4, v5
	v_pk_mul_f32 v[4:5], v[26:27], v[14:15] op_sel_hi:[0,1]
	v_pk_mul_f32 v[12:13], v[26:27], v[12:13] op_sel_hi:[0,1]
	v_mul_f32_e32 v9, v13, v13
	v_mul_f32_e32 v14, v5, v5
	v_fmac_f32_e32 v9, v12, v12
	v_fmac_f32_e32 v14, v4, v4
	v_add_f32_e32 v9, v9, v14
	v_add_f32_e32 v18, v8, v9
	v_pk_mul_f32 v[8:9], v[26:27], v[24:25] op_sel_hi:[0,1]
	v_pk_mul_f32 v[14:15], v[26:27], v[22:23] op_sel_hi:[0,1]
	v_mul_f32_e32 v19, v15, v15
	v_mul_f32_e32 v20, v9, v9
	v_fmac_f32_e32 v19, v14, v14
	v_fmac_f32_e32 v20, v8, v8
	v_add_f32_e32 v19, v19, v20
	v_add_f32_e32 v18, v18, v19
	ds_bpermute_b32 v16, v16, v18
	s_waitcnt lgkmcnt(0)
	v_add_f32_e32 v18, v18, v16
	ds_bpermute_b32 v19, v17, v18
	v_or_b32_e32 v16, s44, v28
	v_ashrrev_i32_e32 v17, 31, v16
	s_and_saveexec_b64 s[20:21], s[4:5]
	s_cbranch_execz .LBB0_336
	s_waitcnt lgkmcnt(0)
	v_add_f32_e32 v20, v18, v19
	v_lshlrev_b64 v[18:19], 5, v[16:17]
	v_lshl_add_u64 v[18:19], s[12:13], 0, v[18:19]
	s_lshl_b32 s16, s42, 2
	v_lshl_add_u64 v[18:19], v[18:19], 0, s[16:17]
	global_store_dword v[18:19], v20, off
	s_branch .LBB0_336
.LBB0_347:
	s_waitcnt vmcnt(0)
	s_barrier
